# attention: LDS-transposed dwordx4 epilogue + LDS-DMA issue moved to loop top + QK reads pipelined
# speedup vs baseline: 1.0216x; 1.0195x over previous
.LBB0_717:
	s_add_i32 s6, s60, 6
	s_cmp_lt_u32 s6, s55
	s_cselect_b32 s6, s6, s58
	s_mul_i32 s63, s61, 0xa000
	s_lshl_b32 s6, s6, 6
	s_add_i32 s63, s63, 0
	s_add_i32 s75, s63, s30
	s_lshl_b64 s[64:65], s[6:7], 12
	s_add_u32 s66, s10, s64
	s_addc_u32 s67, s11, s65
	s_add_u32 s64, s12, s64
	v_lshl_add_u64 v[2:3], s[66:67], 0, v[172:173]
	s_mov_b32 m0, s75
	s_addc_u32 s65, s13, s65
	global_load_lds_dwordx4 v[2:3], off
	v_lshl_add_u64 v[2:3], s[66:67], 0, v[170:171]
	s_add_i32 m0, s75, 0x400
	s_lshl_b64 s[66:67], s[6:7], 7
	s_add_i32 s6, s63, s34
	global_load_lds_dwordx4 v[2:3], off
	v_lshl_add_u64 v[2:3], v[178:179], 0, s[66:67]
	s_add_i32 m0, s6, 0x4000
	s_nop 0
	global_load_lds_dwordx4 v[2:3], off
	v_lshl_add_u64 v[2:3], s[64:65], 0, v[168:169]
	s_add_i32 m0, s75, 0x6000
	s_nop 0
	global_load_lds_dwordx4 v[2:3], off
	v_lshl_add_u64 v[2:3], s[64:65], 0, v[166:167]
	s_add_i32 m0, s75, 0x6400
	s_nop 0
	global_load_lds_dwordx4 v[2:3], off
	s_sub_i32 s6, s53, 63
	s_cmp_le_u32 s6, s59
	s_cselect_b64 s[18:19], -1, 0
	s_cmp_gt_u32 s6, s59
	s_mul_i32 s62, s54, 0xa000
	s_cbranch_scc1 .LBB0_719
	v_add_u32_e32 v1, s62, v195
	v_add_u32_e32 v13, s62, v204
	v_add_u32_e32 v14, v1, v196
	ds_read_b128 v[2:5], v14
	ds_read_b128 v[6:9], v14 offset:8192
	v_add_u32_e32 v15, v1, v197
	ds_read_b128 v[220:223], v15
	ds_read_b128 v[224:227], v15 offset:8192
	v_add_u32_e32 v14, v1, v198
	ds_read_b128 v[228:231], v14
	ds_read_b128 v[232:235], v14 offset:8192
	s_waitcnt lgkmcnt(4)
	v_mfma_f32_32x32x16_bf16 v[16:31], v[2:5], v[112:115], 0
	v_mfma_f32_32x32x16_bf16 v[32:47], v[6:9], v[112:115], 0
	v_add_u32_e32 v15, v1, v199
	ds_read_b128 v[236:239], v15
	ds_read_b128 v[240:243], v15 offset:8192
	s_waitcnt lgkmcnt(4)
	v_mfma_f32_32x32x16_bf16 v[16:31], v[220:223], v[116:119], v[16:31]
	v_mfma_f32_32x32x16_bf16 v[32:47], v[224:227], v[116:119], v[32:47]
	v_add_u32_e32 v14, v1, v200
	ds_read_b128 v[2:5], v14
	ds_read_b128 v[6:9], v14 offset:8192
	s_waitcnt lgkmcnt(4)
	v_mfma_f32_32x32x16_bf16 v[16:31], v[228:231], v[120:123], v[16:31]
	v_mfma_f32_32x32x16_bf16 v[32:47], v[232:235], v[120:123], v[32:47]
	v_add_u32_e32 v15, v1, v201
	ds_read_b128 v[220:223], v15
	ds_read_b128 v[224:227], v15 offset:8192
	s_waitcnt lgkmcnt(4)
	v_mfma_f32_32x32x16_bf16 v[16:31], v[236:239], v[124:127], v[16:31]
	v_mfma_f32_32x32x16_bf16 v[32:47], v[240:243], v[124:127], v[32:47]
	v_add_u32_e32 v14, v1, v202
	ds_read_b128 v[228:231], v14
	ds_read_b128 v[232:235], v14 offset:8192
	s_waitcnt lgkmcnt(4)
	v_mfma_f32_32x32x16_bf16 v[16:31], v[2:5], v[128:131], v[16:31]
	v_mfma_f32_32x32x16_bf16 v[32:47], v[6:9], v[128:131], v[32:47]
	v_add_u32_e32 v15, v1, v203
	ds_read_b128 v[236:239], v15
	ds_read_b128 v[240:243], v15 offset:8192
	s_waitcnt lgkmcnt(4)
	v_mfma_f32_32x32x16_bf16 v[16:31], v[220:223], v[132:135], v[16:31]
	v_mfma_f32_32x32x16_bf16 v[32:47], v[224:227], v[132:135], v[32:47]
	v_add_u32_e32 v14, v13, v205
	ds_read_b128 v[2:5], v14 offset:16384
	ds_read_b128 v[6:9], v14 offset:20480
	s_waitcnt lgkmcnt(4)
	v_mfma_f32_32x32x16_bf16 v[16:31], v[228:231], v[136:139], v[16:31]
	v_mfma_f32_32x32x16_bf16 v[32:47], v[232:235], v[136:139], v[32:47]
	v_add_u32_e32 v15, v13, v206
	ds_read_b128 v[220:223], v15 offset:16384
	ds_read_b128 v[224:227], v15 offset:20480
	s_waitcnt lgkmcnt(4)
	v_mfma_f32_32x32x16_bf16 v[16:31], v[236:239], v[140:143], v[16:31]
	v_mfma_f32_32x32x16_bf16 v[32:47], v[240:243], v[140:143], v[32:47]
	v_add_u32_e32 v14, v13, v207
	ds_read_b128 v[228:231], v14 offset:16384
	ds_read_b128 v[232:235], v14 offset:20480
	s_waitcnt lgkmcnt(4)
	v_mfma_f32_32x32x16_bf16 v[16:31], v[2:5], v[144:147], v[16:31]
	v_mfma_f32_32x32x16_bf16 v[32:47], v[6:9], v[144:147], v[32:47]
	v_add_u32_e32 v15, v13, v208
	ds_read_b128 v[236:239], v15 offset:16384
	ds_read_b128 v[240:243], v15 offset:20480
	s_waitcnt lgkmcnt(4)
	v_mfma_f32_32x32x16_bf16 v[16:31], v[220:223], v[148:151], v[16:31]
	v_mfma_f32_32x32x16_bf16 v[32:47], v[224:227], v[148:151], v[32:47]
	s_waitcnt lgkmcnt(2)
	v_mfma_f32_32x32x16_bf16 v[16:31], v[228:231], v[152:155], v[16:31]
	v_mfma_f32_32x32x16_bf16 v[32:47], v[232:235], v[152:155], v[32:47]
	s_waitcnt lgkmcnt(0)
	v_mfma_f32_32x32x16_bf16 v[16:31], v[236:239], v[156:159], v[16:31]
	v_mfma_f32_32x32x16_bf16 v[32:47], v[240:243], v[156:159], v[32:47]
.LBB0_719:
	s_andn2_b64 vcc, exec, s[18:19]
	s_cbranch_vccnz .LBB0_716
	s_cmp_le_u32 s53, s59
	s_cbranch_scc1 .LBB0_722
	v_cmp_gt_u32_e32 vcc, 2.0, v216
	v_add_u32_e32 v1, 0xbfffffe0, v216
	s_nop 0
	v_cndmask_b32_e32 v16, v215, v16, vcc
	v_cmp_lt_u32_e32 vcc, s39, v1
	v_add_u32_e32 v1, 0xbfffffff, v216
	s_nop 0
	v_cndmask_b32_e32 v32, v215, v32, vcc
	v_cmp_lt_u32_e32 vcc, s39, v1
	v_add_u32_e32 v1, 0xbfffffdf, v216
	s_nop 0
	v_cndmask_b32_e32 v17, v215, v17, vcc
	v_cmp_lt_u32_e32 vcc, s39, v1
	v_add_u32_e32 v1, 0xbffffffe, v216
	s_nop 0
	v_cndmask_b32_e32 v33, v215, v33, vcc
	v_cmp_lt_u32_e32 vcc, s39, v1
	v_add_u32_e32 v1, 0xbfffffde, v216
	s_nop 0
	v_cndmask_b32_e32 v18, v215, v18, vcc
	v_cmp_lt_u32_e32 vcc, s39, v1
	v_add_u32_e32 v1, 0xbffffffd, v216
	s_nop 0
	v_cndmask_b32_e32 v34, v215, v34, vcc
	v_cmp_lt_u32_e32 vcc, s39, v1
	v_add_u32_e32 v1, 0xbfffffdd, v216
	s_nop 0
	v_cndmask_b32_e32 v19, v215, v19, vcc
	v_cmp_lt_u32_e32 vcc, s39, v1
	v_add_u32_e32 v1, 0xbffffff8, v216
	s_nop 0
	v_cndmask_b32_e32 v35, v215, v35, vcc
	v_cmp_lt_u32_e32 vcc, s39, v1
	v_add_u32_e32 v1, 0xbfffffd8, v216
	s_nop 0
	v_cndmask_b32_e32 v20, v215, v20, vcc
	v_cmp_lt_u32_e32 vcc, s39, v1
	v_add_u32_e32 v1, 0xbffffff7, v216
	s_nop 0
	v_cndmask_b32_e32 v36, v215, v36, vcc
	v_cmp_lt_u32_e32 vcc, s39, v1
	v_add_u32_e32 v1, 0xbfffffd7, v216
	s_nop 0
	v_cndmask_b32_e32 v21, v215, v21, vcc
	v_cmp_lt_u32_e32 vcc, s39, v1
	v_add_u32_e32 v1, 0xbffffff6, v216
	s_nop 0
	v_cndmask_b32_e32 v37, v215, v37, vcc
	v_cmp_lt_u32_e32 vcc, s39, v1
	v_add_u32_e32 v1, 0xbfffffd6, v216
	s_nop 0
	v_cndmask_b32_e32 v22, v215, v22, vcc
	v_cmp_lt_u32_e32 vcc, s39, v1
	v_add_u32_e32 v1, 0xbffffff5, v216
	s_nop 0
	v_cndmask_b32_e32 v38, v215, v38, vcc
	v_cmp_lt_u32_e32 vcc, s39, v1
	v_add_u32_e32 v1, 0xbfffffd5, v216
	s_nop 0
	v_cndmask_b32_e32 v23, v215, v23, vcc
	v_cmp_lt_u32_e32 vcc, s39, v1
	v_add_u32_e32 v1, 0xbffffff0, v216
	s_nop 0
	v_cndmask_b32_e32 v39, v215, v39, vcc
	v_cmp_lt_u32_e32 vcc, s39, v1
	v_add_u32_e32 v1, 0xbfffffd0, v216
	s_nop 0
	v_cndmask_b32_e32 v24, v215, v24, vcc
	v_cmp_lt_u32_e32 vcc, s39, v1
	v_add_u32_e32 v1, 0xbfffffef, v216
	s_nop 0
	v_cndmask_b32_e32 v40, v215, v40, vcc
	v_cmp_lt_u32_e32 vcc, s39, v1
	v_add_u32_e32 v1, 0xbfffffcf, v216
	s_nop 0
	v_cndmask_b32_e32 v25, v215, v25, vcc
	v_cmp_lt_u32_e32 vcc, s39, v1
	v_add_u32_e32 v1, 0xbfffffee, v216
	s_nop 0
	v_cndmask_b32_e32 v41, v215, v41, vcc
	v_cmp_lt_u32_e32 vcc, s39, v1
	v_add_u32_e32 v1, 0xbfffffce, v216
	s_nop 0
	v_cndmask_b32_e32 v26, v215, v26, vcc
	v_cmp_lt_u32_e32 vcc, s39, v1
	v_add_u32_e32 v1, 0xbfffffed, v216
	s_nop 0
	v_cndmask_b32_e32 v42, v215, v42, vcc
	v_cmp_lt_u32_e32 vcc, s39, v1
	v_add_u32_e32 v1, 0xbfffffcd, v216
	s_nop 0
	v_cndmask_b32_e32 v27, v215, v27, vcc
	v_cmp_lt_u32_e32 vcc, s39, v1
	v_add_u32_e32 v1, 0xbfffffe8, v216
	s_nop 0
	v_cndmask_b32_e32 v43, v215, v43, vcc
	v_cmp_lt_u32_e32 vcc, s39, v1
	v_add_u32_e32 v1, 0xbfffffc8, v216
	s_nop 0
	v_cndmask_b32_e32 v28, v215, v28, vcc
	v_cmp_lt_u32_e32 vcc, s39, v1
	v_add_u32_e32 v1, 0xbfffffe7, v216
	s_nop 0
	v_cndmask_b32_e32 v44, v215, v44, vcc
	v_cmp_lt_u32_e32 vcc, s39, v1
	v_add_u32_e32 v1, 0xbfffffc7, v216
	s_nop 0
	v_cndmask_b32_e32 v29, v215, v29, vcc
	v_cmp_lt_u32_e32 vcc, s39, v1
	v_add_u32_e32 v1, 0xbfffffe6, v216
	s_nop 0
	v_cndmask_b32_e32 v45, v215, v45, vcc
	v_cmp_lt_u32_e32 vcc, s39, v1
	v_add_u32_e32 v1, 0xbfffffc6, v216
	s_nop 0
	v_cndmask_b32_e32 v30, v215, v30, vcc
	v_cmp_lt_u32_e32 vcc, s39, v1
	v_add_u32_e32 v1, 0xbfffffe5, v216
	s_nop 0
	v_cndmask_b32_e32 v46, v215, v46, vcc
	v_cmp_lt_u32_e32 vcc, s39, v1
	v_add_u32_e32 v1, 0xbfffffc5, v216
	s_nop 0
	v_cndmask_b32_e32 v31, v215, v31, vcc
	v_cmp_lt_u32_e32 vcc, s39, v1
	s_nop 1
	v_cndmask_b32_e32 v47, v215, v47, vcc

.LBB0_725:
	s_waitcnt vmcnt(0)
	s_and_saveexec_b64 s[18:19], s[0:1]
	ds_write_b32 v209, v218
	s_or_b64 exec, exec, s[18:19]
	v_mbcnt_lo_u32_b32 v1, -1, 0
	v_mbcnt_hi_u32_b32 v1, -1, v1
	s_lshl_b32 s98, s33, 11
	s_mov_b32 s99, 0x5040100
	s_mov_b32 s100, 0x7060302
	s_waitcnt lgkmcnt(0)
	ds_read_b128 v[32:35], v211
	ds_read_b128 v[36:39], v211 offset:32
	ds_read_b128 v[40:43], v211 offset:64
	ds_read_b128 v[44:47], v211 offset:96
	s_lshl_b64 s[16:17], s[16:17], 12
	s_add_u32 s16, s45, s16
	s_addc_u32 s17, s47, s17
	v_lshrrev_b32_e32 v2, 5, v1
	v_and_b32_e32 v3, 31, v1
	v_lshlrev_b32_e32 v2, 10, v2
	v_lshl_add_u32 v2, v3, 2, v2
	v_add_u32_e32 v2, s98, v2
	v_lshrrev_b32_e32 v4, 4, v1
	v_and_b32_e32 v5, 15, v1
	v_lshlrev_b32_e32 v6, 9, v4
	v_lshl_add_u32 v6, v5, 5, v6
	v_add_u32_e32 v6, s98, v6
	v_lshlrev_b32_e32 v7, 13, v4
	v_lshl_add_u32 v7, v5, 4, v7
	v_add_u32_e32 v3, 0xa000, v2
	v_add_u32_e32 v8, 0xa000, v6
	s_waitcnt lgkmcnt(0)
	v_rcp_f32_e32 v16, v32
	v_rcp_f32_e32 v17, v33
	v_rcp_f32_e32 v18, v34
	v_rcp_f32_e32 v19, v35
	v_rcp_f32_e32 v20, v36
	v_rcp_f32_e32 v21, v37
	v_rcp_f32_e32 v22, v38
	v_rcp_f32_e32 v23, v39
	v_rcp_f32_e32 v24, v40
	v_rcp_f32_e32 v25, v41
	v_rcp_f32_e32 v26, v42
	v_rcp_f32_e32 v27, v43
	v_rcp_f32_e32 v28, v44
	v_rcp_f32_e32 v29, v45
	v_rcp_f32_e32 v30, v46
	v_rcp_f32_e32 v31, v47
	s_nop 0
	v_pk_mul_f32 v[96:97], v[96:97], v[16:17]
	v_pk_mul_f32 v[80:81], v[80:81], v[16:17]
	v_pk_mul_f32 v[64:65], v[64:65], v[16:17]
	v_pk_mul_f32 v[48:49], v[48:49], v[16:17]
	v_cvt_pk_bf16_f32 v96, v96, v97
	v_cvt_pk_bf16_f32 v80, v80, v81
	v_cvt_pk_bf16_f32 v64, v64, v65
	v_cvt_pk_bf16_f32 v48, v48, v49
	ds_write_b32 v2, v96
	ds_write_b32 v2, v80 offset:128
	ds_write_b32 v2, v64 offset:256
	ds_write_b32 v2, v48 offset:384
	v_pk_mul_f32 v[98:99], v[98:99], v[18:19]
	v_pk_mul_f32 v[82:83], v[82:83], v[18:19]
	v_pk_mul_f32 v[66:67], v[66:67], v[18:19]
	v_pk_mul_f32 v[50:51], v[50:51], v[18:19]
	v_cvt_pk_bf16_f32 v98, v98, v99
	v_cvt_pk_bf16_f32 v82, v82, v83
	v_cvt_pk_bf16_f32 v66, v66, v67
	v_cvt_pk_bf16_f32 v50, v50, v51
	ds_write_b32 v2, v98 offset:512
	ds_write_b32 v2, v82 offset:640
	ds_write_b32 v2, v66 offset:768
	ds_write_b32 v2, v50 offset:896
	v_pk_mul_f32 v[100:101], v[100:101], v[20:21]
	v_pk_mul_f32 v[84:85], v[84:85], v[20:21]
	v_pk_mul_f32 v[68:69], v[68:69], v[20:21]
	v_pk_mul_f32 v[52:53], v[52:53], v[20:21]
	v_cvt_pk_bf16_f32 v100, v100, v101
	v_cvt_pk_bf16_f32 v84, v84, v85
	v_cvt_pk_bf16_f32 v68, v68, v69
	v_cvt_pk_bf16_f32 v52, v52, v53
	ds_write_b32 v2, v100 offset:24576
	ds_write_b32 v2, v84 offset:24704
	ds_write_b32 v2, v68 offset:24832
	ds_write_b32 v2, v52 offset:24960
	v_pk_mul_f32 v[102:103], v[102:103], v[22:23]
	v_pk_mul_f32 v[86:87], v[86:87], v[22:23]
	v_pk_mul_f32 v[70:71], v[70:71], v[22:23]
	v_pk_mul_f32 v[54:55], v[54:55], v[22:23]
	v_cvt_pk_bf16_f32 v102, v102, v103
	v_cvt_pk_bf16_f32 v86, v86, v87
	v_cvt_pk_bf16_f32 v70, v70, v71
	v_cvt_pk_bf16_f32 v54, v54, v55
	ds_write_b32 v2, v102 offset:25088
	ds_write_b32 v2, v86 offset:25216
	ds_write_b32 v2, v70 offset:25344
	ds_write_b32 v2, v54 offset:25472
	v_pk_mul_f32 v[104:105], v[104:105], v[24:25]
	v_pk_mul_f32 v[88:89], v[88:89], v[24:25]
	v_pk_mul_f32 v[72:73], v[72:73], v[24:25]
	v_pk_mul_f32 v[56:57], v[56:57], v[24:25]
	v_cvt_pk_bf16_f32 v104, v104, v105
	v_cvt_pk_bf16_f32 v88, v88, v89
	v_cvt_pk_bf16_f32 v72, v72, v73
	v_cvt_pk_bf16_f32 v56, v56, v57
	ds_write_b32 v3, v104
	ds_write_b32 v3, v88 offset:128
	ds_write_b32 v3, v72 offset:256
	ds_write_b32 v3, v56 offset:384
	v_pk_mul_f32 v[106:107], v[106:107], v[26:27]
	v_pk_mul_f32 v[90:91], v[90:91], v[26:27]
	v_pk_mul_f32 v[74:75], v[74:75], v[26:27]
	v_pk_mul_f32 v[58:59], v[58:59], v[26:27]
	v_cvt_pk_bf16_f32 v106, v106, v107
	v_cvt_pk_bf16_f32 v90, v90, v91
	v_cvt_pk_bf16_f32 v74, v74, v75
	v_cvt_pk_bf16_f32 v58, v58, v59
	ds_write_b32 v3, v106 offset:512
	ds_write_b32 v3, v90 offset:640
	ds_write_b32 v3, v74 offset:768
	ds_write_b32 v3, v58 offset:896
	v_pk_mul_f32 v[108:109], v[108:109], v[28:29]
	v_pk_mul_f32 v[92:93], v[92:93], v[28:29]
	v_pk_mul_f32 v[76:77], v[76:77], v[28:29]
	v_pk_mul_f32 v[60:61], v[60:61], v[28:29]
	v_cvt_pk_bf16_f32 v108, v108, v109
	v_cvt_pk_bf16_f32 v92, v92, v93
	v_cvt_pk_bf16_f32 v76, v76, v77
	v_cvt_pk_bf16_f32 v60, v60, v61
	ds_write_b32 v3, v108 offset:24576
	ds_write_b32 v3, v92 offset:24704
	ds_write_b32 v3, v76 offset:24832
	ds_write_b32 v3, v60 offset:24960
	v_pk_mul_f32 v[110:111], v[110:111], v[30:31]
	v_pk_mul_f32 v[94:95], v[94:95], v[30:31]
	v_pk_mul_f32 v[78:79], v[78:79], v[30:31]
	v_pk_mul_f32 v[62:63], v[62:63], v[30:31]
	v_cvt_pk_bf16_f32 v110, v110, v111
	v_cvt_pk_bf16_f32 v94, v94, v95
	v_cvt_pk_bf16_f32 v78, v78, v79
	v_cvt_pk_bf16_f32 v62, v62, v63
	ds_write_b32 v3, v110 offset:25088
	ds_write_b32 v3, v94 offset:25216
	ds_write_b32 v3, v78 offset:25344
	ds_write_b32 v3, v62 offset:25472
	s_waitcnt lgkmcnt(0)
	ds_read_b128 v[112:115], v6
	ds_read_b128 v[116:119], v6 offset:16
	ds_read_b128 v[120:123], v6 offset:24576
	ds_read_b128 v[124:127], v6 offset:24592
	ds_read_b128 v[128:131], v8
	ds_read_b128 v[132:135], v8 offset:16
	ds_read_b128 v[136:139], v8 offset:24576
	ds_read_b128 v[140:143], v8 offset:24592
	s_waitcnt lgkmcnt(6)
	v_perm_b32 v16, v113, v112, s99
	v_perm_b32 v17, v115, v114, s99
	v_perm_b32 v18, v117, v116, s99
	v_perm_b32 v19, v119, v118, s99
	v_perm_b32 v20, v113, v112, s100
	v_perm_b32 v21, v115, v114, s100
	v_perm_b32 v22, v117, v116, s100
	v_perm_b32 v23, v119, v118, s100
	global_store_dwordx4 v7, v[16:19], s[16:17]
	v_add_u32_e32 v10, 0x1000, v7
	global_store_dwordx4 v10, v[20:23], s[16:17]
	s_waitcnt lgkmcnt(4)
	v_perm_b32 v24, v121, v120, s99
	v_perm_b32 v25, v123, v122, s99
	v_perm_b32 v26, v125, v124, s99
	v_perm_b32 v27, v127, v126, s99
	v_perm_b32 v28, v121, v120, s100
	v_perm_b32 v29, v123, v122, s100
	v_perm_b32 v30, v125, v124, s100
	v_perm_b32 v31, v127, v126, s100
	v_add_u32_e32 v9, 0x8000, v7
	global_store_dwordx4 v9, v[24:27], s[16:17]
	v_add_u32_e32 v10, 0x9000, v7
	global_store_dwordx4 v10, v[28:31], s[16:17]
	s_waitcnt lgkmcnt(2)
	v_perm_b32 v32, v129, v128, s99
	v_perm_b32 v33, v131, v130, s99
	v_perm_b32 v34, v133, v132, s99
	v_perm_b32 v35, v135, v134, s99
	v_perm_b32 v36, v129, v128, s100
	v_perm_b32 v37, v131, v130, s100
	v_perm_b32 v38, v133, v132, s100
	v_perm_b32 v39, v135, v134, s100
	v_add_u32_e32 v9, 0x10000, v7
	global_store_dwordx4 v9, v[32:35], s[16:17]
	v_add_u32_e32 v10, 0x11000, v7
	global_store_dwordx4 v10, v[36:39], s[16:17]
	s_waitcnt lgkmcnt(0)
	v_perm_b32 v40, v137, v136, s99
	v_perm_b32 v41, v139, v138, s99
	v_perm_b32 v42, v141, v140, s99
	v_perm_b32 v43, v143, v142, s99
	v_perm_b32 v44, v137, v136, s100
	v_perm_b32 v45, v139, v138, s100
	v_perm_b32 v46, v141, v140, s100
	v_perm_b32 v47, v143, v142, s100
	v_add_u32_e32 v9, 0x18000, v7
	global_store_dwordx4 v9, v[40:43], s[16:17]
	v_add_u32_e32 v10, 0x19000, v7
	global_store_dwordx4 v10, v[44:47], s[16:17]
	s_branch .LBB0_712

.LBB0_1511:
	s_add_i32 s26, s81, 6
	s_cmp_lt_u32 s26, s79
	s_cselect_b32 s26, s26, s85
	s_lshl_b32 s26, s26, 6
	s_lshl_b32 s87, s82, 15
	s_add_i32 s87, s50, s87
	s_lshl_b64 s[88:89], s[26:27], 12
	s_add_u32 s90, s30, s88
	s_addc_u32 s91, s31, s89
	s_add_u32 s88, s34, s88
	v_lshl_add_u64 v[2:3], s[90:91], 0, v[154:155]
	s_mov_b32 m0, s87
	s_addc_u32 s89, s35, s89
	global_load_lds_dwordx4 v[2:3], off
	v_lshl_add_u64 v[2:3], s[90:91], 0, v[152:153]
	s_add_i32 m0, s87, 0x400
	s_nop 0
	global_load_lds_dwordx4 v[2:3], off
	v_lshl_add_u64 v[2:3], s[88:89], 0, v[150:151]
	s_add_i32 m0, s87, 0x4000
	s_nop 0
	global_load_lds_dwordx4 v[2:3], off
	v_lshl_add_u64 v[2:3], s[88:89], 0, v[148:149]
	s_add_i32 m0, s87, 0x4400
	s_nop 0
	global_load_lds_dwordx4 v[2:3], off
	s_sub_i32 s26, s83, 63
	s_cmp_le_u32 s26, s86
	s_cselect_b64 s[38:39], -1, 0
	s_cmp_gt_u32 s26, s86
	s_cbranch_scc1 .LBB0_1513
	v_lshl_add_u32 v1, s80, 15, v178
	ds_read_b128 v[16:19], v203
	ds_read_b128 v[20:23], v203 offset:32
	ds_read_b128 v[24:27], v203 offset:64
	ds_read_b128 v[28:31], v203 offset:96
	ds_read_b128 v[32:35], v203 offset:128
	ds_read_b128 v[36:39], v203 offset:160
	ds_read_b128 v[40:43], v203 offset:192
	ds_read_b128 v[44:47], v203 offset:224
	v_add_u32_e32 v14, v1, v179
	ds_read_b128 v[2:5], v14
	ds_read_b128 v[6:9], v14 offset:8192
	v_add_u32_e32 v15, v1, v180
	ds_read_b128 v[208:211], v15
	ds_read_b128 v[212:215], v15 offset:8192
	v_add_u32_e32 v14, v1, v181
	ds_read_b128 v[216:219], v14
	ds_read_b128 v[220:223], v14 offset:8192
	s_waitcnt lgkmcnt(4)
	v_mfma_f32_32x32x16_bf16 v[16:31], v[2:5], v[112:115], v[16:31]
	v_mfma_f32_32x32x16_bf16 v[32:47], v[6:9], v[112:115], v[32:47]
	v_add_u32_e32 v15, v1, v182
	ds_read_b128 v[224:227], v15
	ds_read_b128 v[228:231], v15 offset:8192
	s_waitcnt lgkmcnt(4)
	v_mfma_f32_32x32x16_bf16 v[16:31], v[208:211], v[116:119], v[16:31]
	v_mfma_f32_32x32x16_bf16 v[32:47], v[212:215], v[116:119], v[32:47]
	v_add_u32_e32 v14, v1, v183
	ds_read_b128 v[2:5], v14
	ds_read_b128 v[6:9], v14 offset:8192
	s_waitcnt lgkmcnt(4)
	v_mfma_f32_32x32x16_bf16 v[16:31], v[216:219], v[120:123], v[16:31]
	v_mfma_f32_32x32x16_bf16 v[32:47], v[220:223], v[120:123], v[32:47]
	v_add_u32_e32 v15, v1, v184
	ds_read_b128 v[208:211], v15
	ds_read_b128 v[212:215], v15 offset:8192
	s_waitcnt lgkmcnt(4)
	v_mfma_f32_32x32x16_bf16 v[16:31], v[224:227], v[124:127], v[16:31]
	v_mfma_f32_32x32x16_bf16 v[32:47], v[228:231], v[124:127], v[32:47]
	v_add_u32_e32 v14, v1, v185
	ds_read_b128 v[216:219], v14
	ds_read_b128 v[220:223], v14 offset:8192
	s_waitcnt lgkmcnt(4)
	v_mfma_f32_32x32x16_bf16 v[16:31], v[2:5], v[128:131], v[16:31]
	v_mfma_f32_32x32x16_bf16 v[32:47], v[6:9], v[128:131], v[32:47]
	v_add_u32_e32 v15, v1, v186
	ds_read_b128 v[224:227], v15
	ds_read_b128 v[228:231], v15 offset:8192
	s_waitcnt lgkmcnt(4)
	v_mfma_f32_32x32x16_bf16 v[16:31], v[208:211], v[132:135], v[16:31]
	v_mfma_f32_32x32x16_bf16 v[32:47], v[212:215], v[132:135], v[32:47]
	s_waitcnt lgkmcnt(2)
	v_mfma_f32_32x32x16_bf16 v[16:31], v[216:219], v[136:139], v[16:31]
	v_mfma_f32_32x32x16_bf16 v[32:47], v[220:223], v[136:139], v[32:47]
	s_waitcnt lgkmcnt(0)
	v_mfma_f32_32x32x16_bf16 v[16:31], v[224:227], v[140:143], v[16:31]
	v_mfma_f32_32x32x16_bf16 v[32:47], v[228:231], v[140:143], v[32:47]
.LBB0_1513:
	s_andn2_b64 vcc, exec, s[38:39]
	s_cbranch_vccnz .LBB0_1510
	s_cmp_le_u32 s83, s84
	s_cbranch_scc1 .LBB0_1516
	v_cmp_gt_u32_e32 vcc, 2.0, v201
	v_add_u32_e32 v1, 0xbfffffe0, v201
	s_nop 0
	v_cndmask_b32_e32 v16, v200, v16, vcc
	v_cmp_lt_u32_e32 vcc, s61, v1
	v_add_u32_e32 v1, 0xbfffffff, v201
	s_nop 0
	v_cndmask_b32_e32 v32, v200, v32, vcc
	v_cmp_lt_u32_e32 vcc, s61, v1
	v_add_u32_e32 v1, 0xbfffffdf, v201
	s_nop 0
	v_cndmask_b32_e32 v17, v200, v17, vcc
	v_cmp_lt_u32_e32 vcc, s61, v1
	v_add_u32_e32 v1, 0xbffffffe, v201
	s_nop 0
	v_cndmask_b32_e32 v33, v200, v33, vcc
	v_cmp_lt_u32_e32 vcc, s61, v1
	v_add_u32_e32 v1, 0xbfffffde, v201
	s_nop 0
	v_cndmask_b32_e32 v18, v200, v18, vcc
	v_cmp_lt_u32_e32 vcc, s61, v1
	v_add_u32_e32 v1, 0xbffffffd, v201
	s_nop 0
	v_cndmask_b32_e32 v34, v200, v34, vcc
	v_cmp_lt_u32_e32 vcc, s61, v1
	v_add_u32_e32 v1, 0xbfffffdd, v201
	s_nop 0
	v_cndmask_b32_e32 v19, v200, v19, vcc
	v_cmp_lt_u32_e32 vcc, s61, v1
	v_add_u32_e32 v1, 0xbffffff8, v201
	s_nop 0
	v_cndmask_b32_e32 v35, v200, v35, vcc
	v_cmp_lt_u32_e32 vcc, s61, v1
	v_add_u32_e32 v1, 0xbfffffd8, v201
	s_nop 0
	v_cndmask_b32_e32 v20, v200, v20, vcc
	v_cmp_lt_u32_e32 vcc, s61, v1
	v_add_u32_e32 v1, 0xbffffff7, v201
	s_nop 0
	v_cndmask_b32_e32 v36, v200, v36, vcc
	v_cmp_lt_u32_e32 vcc, s61, v1
	v_add_u32_e32 v1, 0xbfffffd7, v201
	s_nop 0
	v_cndmask_b32_e32 v21, v200, v21, vcc
	v_cmp_lt_u32_e32 vcc, s61, v1
	v_add_u32_e32 v1, 0xbffffff6, v201
	s_nop 0
	v_cndmask_b32_e32 v37, v200, v37, vcc
	v_cmp_lt_u32_e32 vcc, s61, v1
	v_add_u32_e32 v1, 0xbfffffd6, v201
	s_nop 0
	v_cndmask_b32_e32 v22, v200, v22, vcc
	v_cmp_lt_u32_e32 vcc, s61, v1
	v_add_u32_e32 v1, 0xbffffff5, v201
	s_nop 0
	v_cndmask_b32_e32 v38, v200, v38, vcc
	v_cmp_lt_u32_e32 vcc, s61, v1
	v_add_u32_e32 v1, 0xbfffffd5, v201
	s_nop 0
	v_cndmask_b32_e32 v23, v200, v23, vcc
	v_cmp_lt_u32_e32 vcc, s61, v1
	v_add_u32_e32 v1, 0xbffffff0, v201
	s_nop 0
	v_cndmask_b32_e32 v39, v200, v39, vcc
	v_cmp_lt_u32_e32 vcc, s61, v1
	v_add_u32_e32 v1, 0xbfffffd0, v201
	s_nop 0
	v_cndmask_b32_e32 v24, v200, v24, vcc
	v_cmp_lt_u32_e32 vcc, s61, v1
	v_add_u32_e32 v1, 0xbfffffef, v201
	s_nop 0
	v_cndmask_b32_e32 v40, v200, v40, vcc
	v_cmp_lt_u32_e32 vcc, s61, v1
	v_add_u32_e32 v1, 0xbfffffcf, v201
	s_nop 0
	v_cndmask_b32_e32 v25, v200, v25, vcc
	v_cmp_lt_u32_e32 vcc, s61, v1
	v_add_u32_e32 v1, 0xbfffffee, v201
	s_nop 0
	v_cndmask_b32_e32 v41, v200, v41, vcc
	v_cmp_lt_u32_e32 vcc, s61, v1
	v_add_u32_e32 v1, 0xbfffffce, v201
	s_nop 0
	v_cndmask_b32_e32 v26, v200, v26, vcc
	v_cmp_lt_u32_e32 vcc, s61, v1
	v_add_u32_e32 v1, 0xbfffffed, v201
	s_nop 0
	v_cndmask_b32_e32 v42, v200, v42, vcc
	v_cmp_lt_u32_e32 vcc, s61, v1
	v_add_u32_e32 v1, 0xbfffffcd, v201
	s_nop 0
	v_cndmask_b32_e32 v27, v200, v27, vcc
	v_cmp_lt_u32_e32 vcc, s61, v1
	v_add_u32_e32 v1, 0xbfffffe8, v201
	s_nop 0
	v_cndmask_b32_e32 v43, v200, v43, vcc
	v_cmp_lt_u32_e32 vcc, s61, v1
	v_add_u32_e32 v1, 0xbfffffc8, v201
	s_nop 0
	v_cndmask_b32_e32 v28, v200, v28, vcc
	v_cmp_lt_u32_e32 vcc, s61, v1
	v_add_u32_e32 v1, 0xbfffffe7, v201
	s_nop 0
	v_cndmask_b32_e32 v44, v200, v44, vcc
	v_cmp_lt_u32_e32 vcc, s61, v1
	v_add_u32_e32 v1, 0xbfffffc7, v201
	s_nop 0
	v_cndmask_b32_e32 v29, v200, v29, vcc
	v_cmp_lt_u32_e32 vcc, s61, v1
	v_add_u32_e32 v1, 0xbfffffe6, v201
	s_nop 0
	v_cndmask_b32_e32 v45, v200, v45, vcc
	v_cmp_lt_u32_e32 vcc, s61, v1
	v_add_u32_e32 v1, 0xbfffffc6, v201
	s_nop 0
	v_cndmask_b32_e32 v30, v200, v30, vcc
	v_cmp_lt_u32_e32 vcc, s61, v1
	v_add_u32_e32 v1, 0xbfffffe5, v201
	s_nop 0
	v_cndmask_b32_e32 v46, v200, v46, vcc
	v_cmp_lt_u32_e32 vcc, s61, v1
	v_add_u32_e32 v1, 0xbfffffc5, v201
	s_nop 0
	v_cndmask_b32_e32 v31, v200, v31, vcc
	v_cmp_lt_u32_e32 vcc, s61, v1
	s_nop 1
	v_cndmask_b32_e32 v47, v200, v47, vcc

.LBB0_1519:
	s_waitcnt vmcnt(0)
	s_and_saveexec_b64 s[38:39], s[4:5]
	ds_write_b32 v187, v204
	s_or_b64 exec, exec, s[38:39]
	v_mbcnt_lo_u32_b32 v1, -1, 0
	v_mbcnt_hi_u32_b32 v1, -1, v1
	s_lshl_b32 s98, s33, 11
	s_mov_b32 s99, 0x5040100
	s_mov_b32 s100, 0x7060302
	s_waitcnt lgkmcnt(0)
	ds_read_b128 v[32:35], v189
	ds_read_b128 v[36:39], v189 offset:32
	ds_read_b128 v[40:43], v189 offset:64
	ds_read_b128 v[44:47], v189 offset:96
	s_lshl_b64 s[20:21], s[20:21], 1
	s_add_u32 s20, s67, s20
	s_addc_u32 s21, s75, s21
	v_lshrrev_b32_e32 v2, 5, v1
	v_and_b32_e32 v3, 31, v1
	v_lshlrev_b32_e32 v2, 10, v2
	v_lshl_add_u32 v2, v3, 2, v2
	v_add_u32_e32 v2, s98, v2
	v_lshrrev_b32_e32 v4, 4, v1
	v_and_b32_e32 v5, 15, v1
	v_lshlrev_b32_e32 v6, 9, v4
	v_lshl_add_u32 v6, v5, 5, v6
	v_add_u32_e32 v6, s98, v6
	v_lshlrev_b32_e32 v7, 13, v4
	v_lshl_add_u32 v7, v5, 4, v7
	s_waitcnt lgkmcnt(0)
	v_rcp_f32_e32 v16, v32
	v_rcp_f32_e32 v17, v33
	v_rcp_f32_e32 v18, v34
	v_rcp_f32_e32 v19, v35
	v_rcp_f32_e32 v20, v36
	v_rcp_f32_e32 v21, v37
	v_rcp_f32_e32 v22, v38
	v_rcp_f32_e32 v23, v39
	v_rcp_f32_e32 v24, v40
	v_rcp_f32_e32 v25, v41
	v_rcp_f32_e32 v26, v42
	v_rcp_f32_e32 v27, v43
	v_rcp_f32_e32 v28, v44
	v_rcp_f32_e32 v29, v45
	v_rcp_f32_e32 v30, v46
	v_rcp_f32_e32 v31, v47
	s_nop 0
	v_pk_mul_f32 v[96:97], v[96:97], v[16:17]
	v_pk_mul_f32 v[80:81], v[80:81], v[16:17]
	v_pk_mul_f32 v[64:65], v[64:65], v[16:17]
	v_pk_mul_f32 v[48:49], v[48:49], v[16:17]
	v_cvt_pk_bf16_f32 v96, v96, v97
	v_cvt_pk_bf16_f32 v80, v80, v81
	v_cvt_pk_bf16_f32 v64, v64, v65
	v_cvt_pk_bf16_f32 v48, v48, v49
	ds_write_b32 v2, v96
	ds_write_b32 v2, v80 offset:128
	ds_write_b32 v2, v64 offset:256
	ds_write_b32 v2, v48 offset:384
	v_pk_mul_f32 v[98:99], v[98:99], v[18:19]
	v_pk_mul_f32 v[82:83], v[82:83], v[18:19]
	v_pk_mul_f32 v[66:67], v[66:67], v[18:19]
	v_pk_mul_f32 v[50:51], v[50:51], v[18:19]
	v_cvt_pk_bf16_f32 v98, v98, v99
	v_cvt_pk_bf16_f32 v82, v82, v83
	v_cvt_pk_bf16_f32 v66, v66, v67
	v_cvt_pk_bf16_f32 v50, v50, v51
	ds_write_b32 v2, v98 offset:512
	ds_write_b32 v2, v82 offset:640
	ds_write_b32 v2, v66 offset:768
	ds_write_b32 v2, v50 offset:896
	v_pk_mul_f32 v[100:101], v[100:101], v[20:21]
	v_pk_mul_f32 v[84:85], v[84:85], v[20:21]
	v_pk_mul_f32 v[68:69], v[68:69], v[20:21]
	v_pk_mul_f32 v[52:53], v[52:53], v[20:21]
	v_cvt_pk_bf16_f32 v100, v100, v101
	v_cvt_pk_bf16_f32 v84, v84, v85
	v_cvt_pk_bf16_f32 v68, v68, v69
	v_cvt_pk_bf16_f32 v52, v52, v53
	ds_write_b32 v2, v100 offset:16384
	ds_write_b32 v2, v84 offset:16512
	ds_write_b32 v2, v68 offset:16640
	ds_write_b32 v2, v52 offset:16768
	v_pk_mul_f32 v[102:103], v[102:103], v[22:23]
	v_pk_mul_f32 v[86:87], v[86:87], v[22:23]
	v_pk_mul_f32 v[70:71], v[70:71], v[22:23]
	v_pk_mul_f32 v[54:55], v[54:55], v[22:23]
	v_cvt_pk_bf16_f32 v102, v102, v103
	v_cvt_pk_bf16_f32 v86, v86, v87
	v_cvt_pk_bf16_f32 v70, v70, v71
	v_cvt_pk_bf16_f32 v54, v54, v55
	ds_write_b32 v2, v102 offset:16896
	ds_write_b32 v2, v86 offset:17024
	ds_write_b32 v2, v70 offset:17152
	ds_write_b32 v2, v54 offset:17280
	v_pk_mul_f32 v[104:105], v[104:105], v[24:25]
	v_pk_mul_f32 v[88:89], v[88:89], v[24:25]
	v_pk_mul_f32 v[72:73], v[72:73], v[24:25]
	v_pk_mul_f32 v[56:57], v[56:57], v[24:25]
	v_cvt_pk_bf16_f32 v104, v104, v105
	v_cvt_pk_bf16_f32 v88, v88, v89
	v_cvt_pk_bf16_f32 v72, v72, v73
	v_cvt_pk_bf16_f32 v56, v56, v57
	ds_write_b32 v2, v104 offset:32768
	ds_write_b32 v2, v88 offset:32896
	ds_write_b32 v2, v72 offset:33024
	ds_write_b32 v2, v56 offset:33152
	v_pk_mul_f32 v[106:107], v[106:107], v[26:27]
	v_pk_mul_f32 v[90:91], v[90:91], v[26:27]
	v_pk_mul_f32 v[74:75], v[74:75], v[26:27]
	v_pk_mul_f32 v[58:59], v[58:59], v[26:27]
	v_cvt_pk_bf16_f32 v106, v106, v107
	v_cvt_pk_bf16_f32 v90, v90, v91
	v_cvt_pk_bf16_f32 v74, v74, v75
	v_cvt_pk_bf16_f32 v58, v58, v59
	ds_write_b32 v2, v106 offset:33280
	ds_write_b32 v2, v90 offset:33408
	ds_write_b32 v2, v74 offset:33536
	ds_write_b32 v2, v58 offset:33664
	v_pk_mul_f32 v[108:109], v[108:109], v[28:29]
	v_pk_mul_f32 v[92:93], v[92:93], v[28:29]
	v_pk_mul_f32 v[76:77], v[76:77], v[28:29]
	v_pk_mul_f32 v[60:61], v[60:61], v[28:29]
	v_cvt_pk_bf16_f32 v108, v108, v109
	v_cvt_pk_bf16_f32 v92, v92, v93
	v_cvt_pk_bf16_f32 v76, v76, v77
	v_cvt_pk_bf16_f32 v60, v60, v61
	ds_write_b32 v2, v108 offset:49152
	ds_write_b32 v2, v92 offset:49280
	ds_write_b32 v2, v76 offset:49408
	ds_write_b32 v2, v60 offset:49536
	v_pk_mul_f32 v[110:111], v[110:111], v[30:31]
	v_pk_mul_f32 v[94:95], v[94:95], v[30:31]
	v_pk_mul_f32 v[78:79], v[78:79], v[30:31]
	v_pk_mul_f32 v[62:63], v[62:63], v[30:31]
	v_cvt_pk_bf16_f32 v110, v110, v111
	v_cvt_pk_bf16_f32 v94, v94, v95
	v_cvt_pk_bf16_f32 v78, v78, v79
	v_cvt_pk_bf16_f32 v62, v62, v63
	ds_write_b32 v2, v110 offset:49664
	ds_write_b32 v2, v94 offset:49792
	ds_write_b32 v2, v78 offset:49920
	ds_write_b32 v2, v62 offset:50048
	s_waitcnt lgkmcnt(0)
	ds_read_b128 v[112:115], v6
	ds_read_b128 v[116:119], v6 offset:16
	ds_read_b128 v[120:123], v6 offset:16384
	ds_read_b128 v[124:127], v6 offset:16400
	ds_read_b128 v[128:131], v6 offset:32768
	ds_read_b128 v[132:135], v6 offset:32784
	ds_read_b128 v[136:139], v6 offset:49152
	ds_read_b128 v[140:143], v6 offset:49168
	s_waitcnt lgkmcnt(6)
	v_perm_b32 v16, v113, v112, s99
	v_perm_b32 v17, v115, v114, s99
	v_perm_b32 v18, v117, v116, s99
	v_perm_b32 v19, v119, v118, s99
	v_perm_b32 v20, v113, v112, s100
	v_perm_b32 v21, v115, v114, s100
	v_perm_b32 v22, v117, v116, s100
	v_perm_b32 v23, v119, v118, s100
	global_store_dwordx4 v7, v[16:19], s[20:21]
	v_add_u32_e32 v10, 0x1000, v7
	global_store_dwordx4 v10, v[20:23], s[20:21]
	s_waitcnt lgkmcnt(4)
	v_perm_b32 v24, v121, v120, s99
	v_perm_b32 v25, v123, v122, s99
	v_perm_b32 v26, v125, v124, s99
	v_perm_b32 v27, v127, v126, s99
	v_perm_b32 v28, v121, v120, s100
	v_perm_b32 v29, v123, v122, s100
	v_perm_b32 v30, v125, v124, s100
	v_perm_b32 v31, v127, v126, s100
	v_add_u32_e32 v9, 0x8000, v7
	global_store_dwordx4 v9, v[24:27], s[20:21]
	v_add_u32_e32 v10, 0x9000, v7
	global_store_dwordx4 v10, v[28:31], s[20:21]
	s_waitcnt lgkmcnt(2)
	v_perm_b32 v32, v129, v128, s99
	v_perm_b32 v33, v131, v130, s99
	v_perm_b32 v34, v133, v132, s99
	v_perm_b32 v35, v135, v134, s99
	v_perm_b32 v36, v129, v128, s100
	v_perm_b32 v37, v131, v130, s100
	v_perm_b32 v38, v133, v132, s100
	v_perm_b32 v39, v135, v134, s100
	v_add_u32_e32 v9, 0x10000, v7
	global_store_dwordx4 v9, v[32:35], s[20:21]
	v_add_u32_e32 v10, 0x11000, v7
	global_store_dwordx4 v10, v[36:39], s[20:21]
	s_waitcnt lgkmcnt(0)
	v_perm_b32 v40, v137, v136, s99
	v_perm_b32 v41, v139, v138, s99
	v_perm_b32 v42, v141, v140, s99
	v_perm_b32 v43, v143, v142, s99
	v_perm_b32 v44, v137, v136, s100
	v_perm_b32 v45, v139, v138, s100
	v_perm_b32 v46, v141, v140, s100
	v_perm_b32 v47, v143, v142, s100
	v_add_u32_e32 v9, 0x18000, v7
	global_store_dwordx4 v9, v[40:43], s[20:21]
	v_add_u32_e32 v10, 0x19000, v7
	global_store_dwordx4 v10, v[44:47], s[20:21]
	s_branch .LBB0_1483

	.amdhsa_kernel _Z8mega_fwd4Args
		.amdhsa_group_segment_fixed_size 0
		.amdhsa_private_segment_fixed_size 0
		.amdhsa_kernarg_size 424
		.amdhsa_user_sgpr_count 2
		.amdhsa_user_sgpr_dispatch_ptr 0
		.amdhsa_user_sgpr_queue_ptr 0
		.amdhsa_user_sgpr_kernarg_segment_ptr 1
		.amdhsa_user_sgpr_dispatch_id 0
		.amdhsa_user_sgpr_kernarg_preload_length 0
		.amdhsa_user_sgpr_kernarg_preload_offset 0
		.amdhsa_user_sgpr_private_segment_size 0
		.amdhsa_uses_dynamic_stack 0
		.amdhsa_enable_private_segment 0
		.amdhsa_system_sgpr_workgroup_id_x 1
		.amdhsa_system_sgpr_workgroup_id_y 0
		.amdhsa_system_sgpr_workgroup_id_z 0
		.amdhsa_system_sgpr_workgroup_info 0
		.amdhsa_system_vgpr_workitem_id 2
		.amdhsa_next_free_vgpr 252
		.amdhsa_next_free_sgpr 101
		.amdhsa_accum_offset 252
		.amdhsa_reserve_vcc 1
		.amdhsa_float_round_mode_32 0
		.amdhsa_float_round_mode_16_64 0
		.amdhsa_float_denorm_mode_32 3
		.amdhsa_float_denorm_mode_16_64 3
		.amdhsa_dx10_clamp 1
		.amdhsa_ieee_mode 1
		.amdhsa_fp16_overflow 0
		.amdhsa_tg_split 0
		.amdhsa_exception_fp_ieee_invalid_op 0
		.amdhsa_exception_fp_denorm_src 0
		.amdhsa_exception_fp_ieee_div_zero 0
		.amdhsa_exception_fp_ieee_overflow 0
		.amdhsa_exception_fp_ieee_underflow 0
		.amdhsa_exception_fp_ieee_inexact 0
		.amdhsa_exception_int_div_zero 0
	.end_amdhsa_kernel

amdhsa.kernels:
  - .agpr_count:     0
    .args:
      - .offset:         0
        .size:           168
        .value_kind:     by_value
      - .offset:         168
        .size:           4
        .value_kind:     hidden_block_count_x
      - .offset:         172
        .size:           4
        .value_kind:     hidden_block_count_y
      - .offset:         176
        .size:           4
        .value_kind:     hidden_block_count_z
      - .offset:         180
        .size:           2
        .value_kind:     hidden_group_size_x
      - .offset:         182
        .size:           2
        .value_kind:     hidden_group_size_y
      - .offset:         184
        .size:           2
        .value_kind:     hidden_group_size_z
      - .offset:         186
        .size:           2
        .value_kind:     hidden_remainder_x
      - .offset:         188
        .size:           2
        .value_kind:     hidden_remainder_y
      - .offset:         190
        .size:           2
        .value_kind:     hidden_remainder_z
      - .offset:         208
        .size:           8
        .value_kind:     hidden_global_offset_x
      - .offset:         216
        .size:           8
        .value_kind:     hidden_global_offset_y
      - .offset:         224
        .size:           8
        .value_kind:     hidden_global_offset_z
      - .offset:         232
        .size:           2
        .value_kind:     hidden_grid_dims
      - .offset:         256
        .size:           8
        .value_kind:     hidden_multigrid_sync_arg
      - .offset:         288
        .size:           4
        .value_kind:     hidden_dynamic_lds_size
    .group_segment_fixed_size: 0
    .kernarg_segment_align: 8
    .kernarg_segment_size: 424
    .language:       OpenCL C
    .language_version:
      - 2
      - 0
    .max_flat_workgroup_size: 512
    .name:           _Z8mega_fwd4Args
    .private_segment_fixed_size: 0
    .sgpr_count:     107
    .sgpr_spill_count: 175
    .symbol:         _Z8mega_fwd4Args.kd
    .uniform_work_group_size: 1
    .uses_dynamic_stack: false
    .vgpr_count:     252
    .vgpr_spill_count: 0
    .wavefront_size: 64
